# mixer A/C softmax: window/ALiBi score math in float domain (6 VALU per score instead of 9-13), mixer A row-max butterfly via v_permlane16/32_swap instead of ds_bpermute
# speedup vs baseline: 1.0053x; 1.0023x over previous
.LBB0_485:
	v_mov_b32_e32 v159, v48
	v_add_u32_e32 v48, s10, v117
	v_add_u32_e32 v49, s11, v116
	ds_read_b128 v[122:125], v49
	v_bitop3_b32 v49, v48, v87, 15 bitop3:0x6c
	v_lshlrev_b32_e32 v49, 4, v49
	v_add3_u32 v49, v118, v49, s11
	ds_read_b128 v[126:129], v49 offset:1024
	v_add_u32_e32 v49, s11, v115
	ds_read_b128 v[130:133], v49
	v_bitop3_b32 v49, v48, v92, 15 bitop3:0x6c
	v_lshlrev_b32_e32 v49, 4, v49
	v_add3_u32 v49, v118, v49, s11
	ds_read_b128 v[134:137], v49 offset:1024
	v_add_u32_e32 v49, s11, v114
	ds_read_b128 v[138:141], v49
	v_bitop3_b32 v49, v48, v93, 15 bitop3:0x6c
	v_lshlrev_b32_e32 v49, 4, v49
	s_waitcnt vmcnt(3) lgkmcnt(4)
	v_mfma_f32_16x16x32_bf16 v[122:125], v[122:125], v[32:35], 0
	v_add3_u32 v49, v118, v49, s11
	ds_read_b128 v[142:145], v49 offset:1024
	v_add_u32_e32 v49, s11, v113
	ds_read_b128 v[146:149], v49
	s_waitcnt vmcnt(2) lgkmcnt(4)
	v_mfma_f32_16x16x32_bf16 v[122:125], v[130:133], v[36:39], v[122:125]
	v_bitop3_b32 v48, v48, v94, 15 bitop3:0x6c
	v_lshlrev_b32_e32 v48, 4, v48
	v_add3_u32 v48, v118, v48, s11
	s_waitcnt vmcnt(1) lgkmcnt(2)
	v_mfma_f32_16x16x32_bf16 v[122:125], v[138:141], v[40:43], v[122:125]
	v_mov_b32_e32 v158, v81
	ds_read_b128 v[150:153], v48 offset:1024
	v_add_u32_e32 v48, s11, v112
	v_add_u32_e32 v50, s11, v104
	v_add_u32_e32 v52, s11, v111
	v_add_u32_e32 v54, s11, v103
	v_add_u32_e32 v56, s11, v110
	v_add_u32_e32 v58, s11, v102
	v_add_u32_e32 v60, s11, v109
	v_add_u32_e32 v62, s11, v101
	v_add_u32_e32 v64, s11, v108
	v_add_u32_e32 v66, s11, v100
	v_add_u32_e32 v68, s11, v107
	v_add_u32_e32 v70, s11, v99
	v_add_u32_e32 v72, s11, v106
	v_add_u32_e32 v74, s11, v98
	v_add_u32_e32 v81, s11, v105
	v_add_u32_e32 v84, s11, v97
	v_add_u32_e32 v133, s10, v96
	ds_read_b64_tr_b16 v[48:49], v48
	ds_read_b64_tr_b16 v[50:51], v50
	ds_read_b64_tr_b16 v[52:53], v52
	ds_read_b64_tr_b16 v[54:55], v54
	ds_read_b64_tr_b16 v[56:57], v56
	ds_read_b64_tr_b16 v[58:59], v58
	ds_read_b64_tr_b16 v[60:61], v60
	ds_read_b64_tr_b16 v[62:63], v62
	ds_read_b64_tr_b16 v[64:65], v64
	ds_read_b64_tr_b16 v[66:67], v66
	ds_read_b64_tr_b16 v[68:69], v68
	ds_read_b64_tr_b16 v[70:71], v70
	ds_read_b64_tr_b16 v[72:73], v72
	ds_read_b64_tr_b16 v[74:75], v74
	ds_read_b64_tr_b16 v[154:155], v81
	ds_read_b64_tr_b16 v[156:157], v84
	v_add_u32_e32 v132, s10, v79
	v_subrev_u32_e32 v84, 64, v133
	v_sub_u32_e32 v130, 64, v133
	s_waitcnt vmcnt(0) lgkmcnt(14)
	v_mfma_f32_16x16x32_bf16 v[122:125], v[146:149], v[44:47], v[122:125]
	v_subrev_u32_e32 v184, 64, v133
	v_cvt_f32_i32_e32 v160, v184
	v_subrev_u32_e32 v184, 64, v132
	v_cmp_gt_u32_e32 vcc, s9, v184
	v_mov_b32_e32 v185, 0xbf800000
	v_mov_b32_e32 v186, 0x42820000
	v_mfma_f32_16x16x32_bf16 v[126:129], v[126:129], v[32:35], 0
	v_add_f32_e32 v161, 1.0, v160
	v_add_f32_e32 v162, 2.0, v160
	v_add_f32_e32 v163, 0x40400000, v160
	v_add_f32_e32 v164, 4.0, v160
	v_add_f32_e32 v165, 0x40a00000, v160
	v_add_f32_e32 v166, 0x40c00000, v160
	v_add_f32_e32 v167, 0x40e00000, v160
	v_cndmask_b32_e32 v185, v185, v186, vcc
	v_mfma_f32_16x16x32_bf16 v[126:129], v[134:137], v[36:39], v[126:129]
	v_mul_f32_e64 v168, |v160|, v85
	v_mul_f32_e64 v169, |v161|, v85
	v_mul_f32_e64 v170, |v162|, v85
	v_mul_f32_e64 v171, |v163|, v85
	v_mul_f32_e64 v172, |v164|, v85
	v_mul_f32_e64 v173, |v165|, v85
	v_mul_f32_e64 v174, |v166|, v85
	v_mul_f32_e64 v175, |v167|, v85
	v_mfma_f32_16x16x32_bf16 v[126:129], v[142:145], v[40:43], v[126:129]
	v_mfma_f32_16x16x32_bf16 v[126:129], v[150:153], v[44:47], v[126:129]
	s_mov_b32 s0, 0xf149f2ca
	v_mul_f32_e32 v176, v80, v122
	v_mul_f32_e32 v177, v80, v123
	v_mul_f32_e32 v178, v80, v124
	v_mul_f32_e32 v179, v80, v125
	v_sub_f32_e32 v176, v176, v168
	v_sub_f32_e32 v177, v177, v169
	v_sub_f32_e32 v178, v178, v170
	v_sub_f32_e32 v179, v179, v171
	v_cmp_gt_f32_e64 vcc, v185, |v160|
	v_cmp_gt_f32_e64 s[20:21], v185, |v161|
	s_nop 0
	v_cndmask_b32_e32 v130, v120, v176, vcc
	v_cndmask_b32_e64 v131, v120, v177, s[20:21]
	v_cmp_gt_f32_e64 vcc, v185, |v162|
	v_cmp_gt_f32_e64 s[20:21], v185, |v163|
	s_nop 0
	v_cndmask_b32_e32 v124, v120, v178, vcc
	v_cndmask_b32_e64 v125, v120, v179, s[20:21]
	v_mul_f32_e32 v180, v80, v126
	v_mul_f32_e32 v181, v80, v127
	v_mul_f32_e32 v182, v80, v128
	v_mul_f32_e32 v183, v80, v129
	v_sub_f32_e32 v180, v180, v172
	v_sub_f32_e32 v181, v181, v173
	v_sub_f32_e32 v182, v182, v174
	v_sub_f32_e32 v183, v183, v175
	v_cmp_gt_f32_e64 vcc, v185, |v164|
	v_cmp_gt_f32_e64 s[20:21], v185, |v165|
	s_nop 0
	v_cndmask_b32_e32 v126, v120, v180, vcc
	v_cndmask_b32_e64 v127, v120, v181, s[20:21]
	v_cmp_gt_f32_e64 vcc, v185, |v166|
	v_cmp_gt_f32_e64 s[20:21], v185, |v167|
	s_nop 0
	v_cndmask_b32_e32 v128, v120, v182, vcc
	v_cndmask_b32_e64 v84, v120, v183, s[20:21]
	v_max3_f32 v134, v130, s0, v131
	v_max3_f32 v134, v134, v124, v125
	v_max3_f32 v134, v134, v126, v127
	v_max3_f32 v81, v134, v128, v84
	s_addk_i32 s11, 0x2000
	s_add_i32 s10, s10, 32
	s_cmpk_eq_u32 s11, 0xa000
	v_mov_b32_e32 v122, v81
	s_nop 1
	v_permlane16_swap_b32_e32 v81, v122
	v_max_f32_e32 v81, v81, v122
	v_mov_b32_e32 v122, v81
	s_nop 1
	v_permlane32_swap_b32_e32 v81, v122
	s_waitcnt lgkmcnt(0)
	v_max3_f32 v81, v158, v81, v122
	v_sub_f32_e32 v123, v130, v81
	v_mul_f32_e32 v123, 0x3fb8aa3b, v123
	v_exp_f32_e32 v129, v123
	v_sub_f32_e32 v123, v131, v81
	v_mul_f32_e32 v123, 0x3fb8aa3b, v123
	v_exp_f32_e32 v130, v123
	v_sub_f32_e32 v123, v124, v81
	v_mul_f32_e32 v123, 0x3fb8aa3b, v123
	v_exp_f32_e32 v131, v123
	v_sub_f32_e32 v123, v125, v81
	v_mul_f32_e32 v123, 0x3fb8aa3b, v123
	v_exp_f32_e32 v132, v123
	v_sub_f32_e32 v123, v126, v81
	v_mul_f32_e32 v123, 0x3fb8aa3b, v123
	v_exp_f32_e32 v126, v123
	v_sub_f32_e32 v123, v127, v81
	v_mul_f32_e32 v123, 0x3fb8aa3b, v123
	v_sub_f32_e32 v122, v158, v81
	v_exp_f32_e32 v127, v123
	v_sub_f32_e32 v123, v128, v81
	v_sub_f32_e32 v84, v84, v81
	v_mul_f32_e32 v122, 0x3fb8aa3b, v122
	v_mul_f32_e32 v123, 0x3fb8aa3b, v123
	v_mul_f32_e32 v84, 0x3fb8aa3b, v84
	v_exp_f32_e32 v128, v123
	v_exp_f32_e32 v133, v84
	v_exp_f32_e32 v84, v122
	v_cvt_pk_bf16_f32 v122, v129, v130
	v_cvt_pk_bf16_f32 v123, v131, v132
	v_cvt_pk_bf16_f32 v124, v126, v127
	v_cvt_pk_bf16_f32 v125, v128, v133
	v_pk_mul_f32 v[30:31], v[30:31], v[84:85] op_sel_hi:[1,0]
	v_pk_mul_f32 v[28:29], v[28:29], v[84:85] op_sel_hi:[1,0]
	v_pk_mul_f32 v[26:27], v[26:27], v[84:85] op_sel_hi:[1,0]
	v_pk_mul_f32 v[24:25], v[24:25], v[84:85] op_sel_hi:[1,0]
	v_mfma_f32_16x16x32_bf16 v[28:31], v[48:51], v[122:125], v[28:31]
	v_add_f32_e32 v48, 0, v129
	v_add_f32_e32 v48, v130, v48
	v_add_f32_e32 v48, v131, v48
	v_add_f32_e32 v48, v132, v48
	v_pk_mul_f32 v[22:23], v[22:23], v[84:85] op_sel_hi:[1,0]
	v_pk_mul_f32 v[20:21], v[20:21], v[84:85] op_sel_hi:[1,0]
	v_pk_mul_f32 v[18:19], v[18:19], v[84:85] op_sel_hi:[1,0]
	v_pk_mul_f32 v[16:17], v[16:17], v[84:85] op_sel_hi:[1,0]
	v_pk_mul_f32 v[14:15], v[14:15], v[84:85] op_sel_hi:[1,0]
	v_pk_mul_f32 v[12:13], v[12:13], v[84:85] op_sel_hi:[1,0]
	v_pk_mul_f32 v[10:11], v[10:11], v[84:85] op_sel_hi:[1,0]
	v_pk_mul_f32 v[8:9], v[8:9], v[84:85] op_sel_hi:[1,0]
	v_pk_mul_f32 v[6:7], v[6:7], v[84:85] op_sel_hi:[1,0]
	v_pk_mul_f32 v[4:5], v[4:5], v[84:85] op_sel_hi:[1,0]
	v_pk_mul_f32 v[2:3], v[2:3], v[84:85] op_sel_hi:[1,0]
	v_pk_mul_f32 v[0:1], v[0:1], v[84:85] op_sel_hi:[1,0]
	v_add_f32_e32 v48, v126, v48
	v_mfma_f32_16x16x32_bf16 v[24:27], v[52:55], v[122:125], v[24:27]
	v_add_f32_e32 v48, v127, v48
	v_add_f32_e32 v48, v128, v48
	v_add_f32_e32 v48, v133, v48
	v_mfma_f32_16x16x32_bf16 v[20:23], v[56:59], v[122:125], v[20:23]
	v_fmac_f32_e32 v48, v159, v84
	v_mfma_f32_16x16x32_bf16 v[16:19], v[60:63], v[122:125], v[16:19]
	v_mfma_f32_16x16x32_bf16 v[12:15], v[64:67], v[122:125], v[12:15]
	v_mfma_f32_16x16x32_bf16 v[8:11], v[68:71], v[122:125], v[8:11]
	v_mfma_f32_16x16x32_bf16 v[4:7], v[72:75], v[122:125], v[4:7]
	v_mfma_f32_16x16x32_bf16 v[0:3], v[154:157], v[122:125], v[0:3]
	s_cbranch_scc0 .LBB0_485
	s_ashr_i32 s9, s8, 31
	s_lshl_b64 s[0:1], s[8:9], 25
	s_add_u32 s0, s62, s0
	s_addc_u32 s1, s63, s1
	s_lshl_b32 s10, s25, 11
	s_add_u32 s0, s0, s10
	s_addc_u32 s1, s1, 0
	s_lshl_b32 s10, s14, 1
	s_add_u32 s0, s0, s10
	s_addc_u32 s1, s1, 0
	v_lshlrev_b64 v[32:33], 11, v[82:83]
	v_lshl_add_u64 v[32:33], s[0:1], 0, v[32:33]
	v_lshl_add_u64 v[34:35], v[32:33], 0, v[76:77]
	ds_bpermute_b32 v32, v90, v48
	s_waitcnt lgkmcnt(0)
	v_add_f32_e32 v32, v48, v32
	ds_bpermute_b32 v33, v91, v32
	s_waitcnt lgkmcnt(0)
	v_add_f32_e32 v32, v32, v33
	v_div_scale_f32 v33, s[0:1], v32, v32, 1.0
	v_rcp_f32_e32 v36, v33
	s_nop 0
	v_fma_f32 v37, -v33, v36, 1.0
	v_fmac_f32_e32 v36, v37, v36
	v_div_scale_f32 v37, vcc, 1.0, v32, 1.0
	v_mul_f32_e32 v38, v37, v36
	v_fma_f32 v39, -v33, v38, v37
	v_fmac_f32_e32 v38, v39, v36
	v_fma_f32 v33, -v33, v38, v37
	v_div_fmas_f32 v33, v33, v36, v38
	v_div_fixup_f32 v36, v33, v32, 1.0
	v_pk_mul_f32 v[28:29], v[28:29], v[36:37] op_sel_hi:[1,0]
	v_pk_mul_f32 v[30:31], v[30:31], v[36:37] op_sel_hi:[1,0]
	v_pk_mul_f32 v[24:25], v[24:25], v[36:37] op_sel_hi:[1,0]
	v_pk_mul_f32 v[26:27], v[26:27], v[36:37] op_sel_hi:[1,0]
	v_pk_mul_f32 v[20:21], v[20:21], v[36:37] op_sel_hi:[1,0]
	v_pk_mul_f32 v[22:23], v[22:23], v[36:37] op_sel_hi:[1,0]
	v_pk_mul_f32 v[16:17], v[16:17], v[36:37] op_sel_hi:[1,0]
	v_pk_mul_f32 v[18:19], v[18:19], v[36:37] op_sel_hi:[1,0]
	v_pk_mul_f32 v[12:13], v[12:13], v[36:37] op_sel_hi:[1,0]
	v_pk_mul_f32 v[14:15], v[14:15], v[36:37] op_sel_hi:[1,0]
	v_pk_mul_f32 v[8:9], v[8:9], v[36:37] op_sel_hi:[1,0]
	v_pk_mul_f32 v[10:11], v[10:11], v[36:37] op_sel_hi:[1,0]
	v_pk_mul_f32 v[4:5], v[4:5], v[36:37] op_sel_hi:[1,0]
	v_pk_mul_f32 v[6:7], v[6:7], v[36:37] op_sel_hi:[1,0]
	v_pk_mul_f32 v[0:1], v[0:1], v[36:37] op_sel_hi:[1,0]
	v_pk_mul_f32 v[2:3], v[2:3], v[36:37] op_sel_hi:[1,0]
	v_cvt_pk_bf16_f32 v28, v28, v29
	v_cvt_pk_bf16_f32 v29, v30, v31
	v_cvt_pk_bf16_f32 v24, v24, v25
	v_cvt_pk_bf16_f32 v25, v26, v27
	v_cvt_pk_bf16_f32 v20, v20, v21
	v_cvt_pk_bf16_f32 v21, v22, v23
	v_cvt_pk_bf16_f32 v16, v16, v17
	v_cvt_pk_bf16_f32 v17, v18, v19
	v_cvt_pk_bf16_f32 v12, v12, v13
	v_cvt_pk_bf16_f32 v13, v14, v15
	v_cvt_pk_bf16_f32 v8, v8, v9
	v_cvt_pk_bf16_f32 v9, v10, v11
	v_cvt_pk_bf16_f32 v4, v4, v5
	v_cvt_pk_bf16_f32 v5, v6, v7
	v_cvt_pk_bf16_f32 v0, v0, v1
	v_cvt_pk_bf16_f32 v1, v2, v3
	global_store_dwordx2 v[34:35], v[28:29], off
	global_store_dwordx2 v[34:35], v[24:25], off offset:32
	global_store_dwordx2 v[34:35], v[20:21], off offset:64
	global_store_dwordx2 v[34:35], v[16:17], off offset:96
	global_store_dwordx2 v[34:35], v[12:13], off offset:128
	global_store_dwordx2 v[34:35], v[8:9], off offset:160
	global_store_dwordx2 v[34:35], v[4:5], off offset:192
	global_store_dwordx2 v[34:35], v[0:1], off offset:224
	s_and_saveexec_b64 s[10:11], s[6:7]
	s_cbranch_execz .LBB0_478
	s_lshl_b64 s[0:1], s[8:9], 19
	s_add_u32 s0, s66, s0
	s_addc_u32 s1, s67, s1
	s_lshl_b32 s8, s25, 5
	s_add_u32 s0, s0, s8
	s_addc_u32 s1, s1, 0
	s_lshl_b32 s8, s24, 2
	s_add_u32 s0, s0, s8
	s_mov_b32 s8, 0x800000
	v_cmp_gt_f32_e32 vcc, s8, v32
	s_addc_u32 s1, s1, 0
	s_nop 0
	v_cndmask_b32_e64 v0, 0, 32, vcc
	v_ldexp_f32 v0, v32, v0
	v_log_f32_e32 v2, v0
	v_lshlrev_b64 v[0:1], 5, v[82:83]
	v_lshl_add_u64 v[0:1], s[0:1], 0, v[0:1]
	s_mov_b32 s0, 0x3f317217
	v_mul_f32_e32 v3, 0x3f317217, v2
	v_fma_f32 v3, v2, s0, -v3
	v_fmac_f32_e32 v3, 0x3377d1cf, v2
	s_mov_b32 s0, 0x7f800000
	v_fmac_f32_e32 v3, 0x3f317217, v2
	v_cmp_lt_f32_e64 s[0:1], |v2|, s0
	s_nop 1
	v_cndmask_b32_e64 v2, v2, v3, s[0:1]
	v_cndmask_b32_e32 v3, 0, v121, vcc
	v_sub_f32_e32 v2, v2, v3
	v_add_f32_e32 v2, v81, v2
	global_store_dword v[0:1], v2, off
	s_branch .LBB0_478

.LBB0_1604:
	v_add_u32_e32 v0, 0, v162
	s_waitcnt lgkmcnt(1)
	v_add_u32_e32 v98, 0, v164
	ds_read_b128 v[122:125], v0
	ds_read_b128 v[118:121], v98
	v_add_u32_e32 v0, 0, v163
	v_add_u32_e32 v98, 0, v165
	ds_read_b128 v[126:129], v0
	ds_read_b128 v[114:117], v98
	v_add_u32_e32 v0, 0, v166
	v_add_u32_e32 v98, 0, v173
	v_add_u32_e32 v99, 0, v167
	s_waitcnt lgkmcnt(4)
	v_add_u32_e32 v100, 0, v172
	ds_read_b64_tr_b16 v[110:111], v0
	ds_read_b64_tr_b16 v[112:113], v98
	ds_read_b64_tr_b16 v[102:103], v99
	ds_read_b64_tr_b16 v[104:105], v100
	v_add_u32_e32 v0, 0, v168
	v_add_u32_e32 v98, 0, v171
	v_add_u32_e32 v99, 0, v169
	v_add_u32_e32 v100, 0, v170
	ds_read_b64_tr_b16 v[106:107], v0
	ds_read_b64_tr_b16 v[108:109], v98
	ds_read_b64_tr_b16 v[98:99], v99
	ds_read_b64_tr_b16 v[100:101], v100
	s_add_i32 s48, s11, s12
	s_add_i32 s47, s48, 0xffffff80
	s_addk_i32 s48, 0xff9f
	s_cmp_lt_i32 s48, s44
	s_cselect_b64 s[8:9], -1, 0
	s_cmp_gt_i32 s47, s13
	s_cselect_b64 s[52:53], -1, 0
	s_or_b64 s[8:9], s[8:9], s[52:53]
	s_and_b64 vcc, exec, s[8:9]
	v_add_u32_e32 v0, s12, v156
	s_cbranch_vccnz .LBB0_1606
	s_waitcnt vmcnt(7) lgkmcnt(11)
	v_mfma_f32_16x16x32_bf16 v[178:181], v[122:125], v[58:61], 0
	v_add_u32_e32 v209, 0xffffff80, v0
	v_cvt_f32_i32_e32 v208, v209
	s_waitcnt vmcnt(6) lgkmcnt(9)
	v_mfma_f32_16x16x32_bf16 v[178:181], v[126:129], v[62:65], v[178:181]
	s_cmpk_lt_u32 s47, 0x800
	s_cselect_b32 s52, 0x43010000, 0xbf800000
	v_add_f32_e32 v193, 1.0, v208
	v_add_f32_e32 v194, 2.0, v208
	v_add_f32_e32 v195, 0x40400000, v208
	v_add_f32_e32 v196, 4.0, v208
	v_add_f32_e32 v197, 0x40a00000, v208
	v_add_f32_e32 v198, 0x40c00000, v208
	v_add_f32_e32 v199, 0x40e00000, v208
	v_mul_f32_e64 v200, |v208|, v137
	v_mul_f32_e64 v201, |v193|, v137
	v_mul_f32_e64 v202, |v194|, v137
	v_mul_f32_e64 v203, |v195|, v137
	v_mul_f32_e64 v204, |v196|, v137
	v_mul_f32_e64 v205, |v197|, v137
	v_mul_f32_e64 v206, |v198|, v137
	v_mul_f32_e64 v207, |v199|, v137
	v_mfma_f32_16x16x32_bf16 v[182:185], v[118:121], v[58:61], 0
	s_waitcnt lgkmcnt(8)
	v_mfma_f32_16x16x32_bf16 v[182:185], v[114:117], v[62:65], v[182:185]
	v_mul_f32_e32 v210, v134, v178
	v_mul_f32_e32 v211, v134, v179
	v_mul_f32_e32 v212, v134, v180
	v_mul_f32_e32 v213, v134, v181
	v_sub_f32_e32 v210, v210, v200
	v_sub_f32_e32 v211, v211, v201
	v_sub_f32_e32 v212, v212, v202
	v_sub_f32_e32 v213, v213, v203
	v_cmp_gt_f32_e64 vcc, s52, |v208|
	v_cmp_gt_f32_e64 s[8:9], s52, |v193|
	s_nop 0
	v_cndmask_b32_e32 v186, v158, v210, vcc
	v_cndmask_b32_e64 v187, v158, v211, s[8:9]
	v_cmp_gt_f32_e64 vcc, s52, |v194|
	v_cmp_gt_f32_e64 s[8:9], s52, |v195|
	s_nop 0
	v_cndmask_b32_e32 v180, v158, v212, vcc
	v_cndmask_b32_e64 v181, v158, v213, s[8:9]
	v_mul_f32_e32 v214, v134, v182
	v_mul_f32_e32 v215, v134, v183
	v_mul_f32_e32 v216, v134, v184
	v_mul_f32_e32 v217, v134, v185
	v_sub_f32_e32 v214, v214, v204
	v_sub_f32_e32 v215, v215, v205
	v_sub_f32_e32 v216, v216, v206
	v_sub_f32_e32 v217, v217, v207
	v_cmp_gt_f32_e64 vcc, s52, |v196|
	v_cmp_gt_f32_e64 s[8:9], s52, |v197|
	s_nop 0
	v_cndmask_b32_e32 v182, v158, v214, vcc
	v_cndmask_b32_e64 v183, v158, v215, s[8:9]
	v_cmp_gt_f32_e64 vcc, s52, |v198|
	v_cmp_gt_f32_e64 s[8:9], s52, |v199|
	s_nop 0
	v_cndmask_b32_e32 v184, v158, v216, vcc
	v_cndmask_b32_e64 v135, v158, v217, s[8:9]
	v_max3_f32 v188, v186, s39, v187
	v_max3_f32 v188, v188, v180, v181
	v_max3_f32 v188, v188, v182, v183
	v_max3_f32 v136, v188, v184, v135
	ds_bpermute_b32 v178, v142, v136
	s_waitcnt lgkmcnt(0)
	v_max_f32_e32 v178, v178, v178
	v_max_f32_e32 v136, v136, v178
	ds_bpermute_b32 v178, v143, v136
	s_waitcnt lgkmcnt(0)
	v_max3_f32 v185, v177, v136, v178
	v_sub_f32_e32 v136, v186, v185
	v_mul_f32_e32 v136, 0x3fb8aa3b, v136
	v_exp_f32_e32 v178, v136
	v_sub_f32_e32 v136, v187, v185
	v_mul_f32_e32 v136, 0x3fb8aa3b, v136
	v_sub_f32_e32 v180, v180, v185
	v_exp_f32_e32 v179, v136
	v_mul_f32_e32 v180, 0x3fb8aa3b, v180
	v_sub_f32_e32 v181, v181, v185
	v_exp_f32_e32 v180, v180
	v_mul_f32_e32 v181, 0x3fb8aa3b, v181
	v_sub_f32_e32 v182, v182, v185
	v_sub_f32_e32 v136, v177, v185
	v_exp_f32_e32 v181, v181
	v_mul_f32_e32 v182, 0x3fb8aa3b, v182
	v_sub_f32_e32 v183, v183, v185
	v_sub_f32_e32 v184, v184, v185
	v_sub_f32_e32 v135, v135, v185
	v_mul_f32_e32 v136, 0x3fb8aa3b, v136
	v_add_f32_e32 v177, 0, v178
	v_exp_f32_e32 v182, v182
	v_mul_f32_e32 v183, 0x3fb8aa3b, v183
	v_mul_f32_e32 v184, 0x3fb8aa3b, v184
	v_mul_f32_e32 v135, 0x3fb8aa3b, v135
	v_add_f32_e32 v177, v179, v177
	v_exp_f32_e32 v183, v183
	v_exp_f32_e32 v184, v184
	v_exp_f32_e32 v135, v135
	v_exp_f32_e32 v136, v136
	v_add_f32_e32 v177, v180, v177
	v_add_f32_e32 v177, v181, v177
	v_add_f32_e32 v177, v182, v177
	v_add_f32_e32 v177, v183, v177
	v_cvt_pk_bf16_f32 v178, v178, v179
	v_cvt_pk_bf16_f32 v179, v180, v181
	v_cvt_pk_bf16_f32 v180, v182, v183
	v_cvt_pk_bf16_f32 v181, v184, v135
	v_pk_mul_f32 v[88:89], v[88:89], v[136:137] op_sel_hi:[1,0]
	v_pk_mul_f32 v[86:87], v[86:87], v[136:137] op_sel_hi:[1,0]
	v_pk_mul_f32 v[76:77], v[76:77], v[136:137] op_sel_hi:[1,0]
	v_pk_mul_f32 v[74:75], v[74:75], v[136:137] op_sel_hi:[1,0]
	v_pk_mul_f32 v[56:57], v[56:57], v[136:137] op_sel_hi:[1,0]
	v_pk_mul_f32 v[54:55], v[54:55], v[136:137] op_sel_hi:[1,0]
	v_pk_mul_f32 v[52:53], v[52:53], v[136:137] op_sel_hi:[1,0]
	v_pk_mul_f32 v[50:51], v[50:51], v[136:137] op_sel_hi:[1,0]
	v_mfma_f32_16x16x32_bf16 v[86:89], v[110:113], v[178:181], v[86:89]
	v_add_f32_e32 v177, v184, v177
	v_add_f32_e32 v135, v135, v177
	v_fmac_f32_e32 v135, v174, v136
	v_mfma_f32_16x16x32_bf16 v[74:77], v[102:105], v[178:181], v[74:77]
	v_mov_b32_e32 v177, v185
	v_mov_b32_e32 v174, v135
	v_mfma_f32_16x16x32_bf16 v[54:57], v[106:109], v[178:181], v[54:57]
	v_mfma_f32_16x16x32_bf16 v[50:53], v[98:101], v[178:181], v[50:53]
.LBB0_1606:
	s_cmp_lt_i32 s48, s14
	s_cselect_b64 s[8:9], -1, 0
	s_cmp_gt_i32 s47, s15
	s_cselect_b64 s[52:53], -1, 0
	s_or_b64 s[8:9], s[8:9], s[52:53]
	s_and_b64 vcc, exec, s[8:9]
	s_cbranch_vccnz .LBB0_1608
	s_waitcnt vmcnt(5) lgkmcnt(11)
	v_mfma_f32_16x16x32_bf16 v[178:181], v[122:125], v[66:69], 0
	v_add_u32_e32 v209, 0xffffff70, v0
	v_cvt_f32_i32_e32 v208, v209
	s_waitcnt vmcnt(4) lgkmcnt(9)
	v_mfma_f32_16x16x32_bf16 v[178:181], v[126:129], v[70:73], v[178:181]
	s_cmpk_lt_u32 s47, 0x800
	s_cselect_b32 s52, 0x43010000, 0xbf800000
	v_add_f32_e32 v193, 1.0, v208
	v_add_f32_e32 v194, 2.0, v208
	v_add_f32_e32 v195, 0x40400000, v208
	v_add_f32_e32 v196, 4.0, v208
	v_add_f32_e32 v197, 0x40a00000, v208
	v_add_f32_e32 v198, 0x40c00000, v208
	v_add_f32_e32 v199, 0x40e00000, v208
	v_mul_f32_e64 v200, |v208|, v137
	v_mul_f32_e64 v201, |v193|, v137
	v_mul_f32_e64 v202, |v194|, v137
	v_mul_f32_e64 v203, |v195|, v137
	v_mul_f32_e64 v204, |v196|, v137
	v_mul_f32_e64 v205, |v197|, v137
	v_mul_f32_e64 v206, |v198|, v137
	v_mul_f32_e64 v207, |v199|, v137
	v_mfma_f32_16x16x32_bf16 v[182:185], v[118:121], v[66:69], 0
	s_waitcnt lgkmcnt(8)
	v_mfma_f32_16x16x32_bf16 v[182:185], v[114:117], v[70:73], v[182:185]
	v_mul_f32_e32 v210, v134, v178
	v_mul_f32_e32 v211, v134, v179
	v_mul_f32_e32 v212, v134, v180
	v_mul_f32_e32 v213, v134, v181
	v_sub_f32_e32 v210, v210, v200
	v_sub_f32_e32 v211, v211, v201
	v_sub_f32_e32 v212, v212, v202
	v_sub_f32_e32 v213, v213, v203
	v_cmp_gt_f32_e64 vcc, s52, |v208|
	v_cmp_gt_f32_e64 s[8:9], s52, |v193|
	s_nop 0
	v_cndmask_b32_e32 v186, v158, v210, vcc
	v_cndmask_b32_e64 v187, v158, v211, s[8:9]
	v_cmp_gt_f32_e64 vcc, s52, |v194|
	v_cmp_gt_f32_e64 s[8:9], s52, |v195|
	s_nop 0
	v_cndmask_b32_e32 v180, v158, v212, vcc
	v_cndmask_b32_e64 v181, v158, v213, s[8:9]
	v_mul_f32_e32 v214, v134, v182
	v_mul_f32_e32 v215, v134, v183
	v_mul_f32_e32 v216, v134, v184
	v_mul_f32_e32 v217, v134, v185
	v_sub_f32_e32 v214, v214, v204
	v_sub_f32_e32 v215, v215, v205
	v_sub_f32_e32 v216, v216, v206
	v_sub_f32_e32 v217, v217, v207
	v_cmp_gt_f32_e64 vcc, s52, |v196|
	v_cmp_gt_f32_e64 s[8:9], s52, |v197|
	s_nop 0
	v_cndmask_b32_e32 v182, v158, v214, vcc
	v_cndmask_b32_e64 v183, v158, v215, s[8:9]
	v_cmp_gt_f32_e64 vcc, s52, |v198|
	v_cmp_gt_f32_e64 s[8:9], s52, |v199|
	s_nop 0
	v_cndmask_b32_e32 v184, v158, v216, vcc
	v_cndmask_b32_e64 v135, v158, v217, s[8:9]
	v_max3_f32 v188, v186, s39, v187
	v_max3_f32 v188, v188, v180, v181
	v_max3_f32 v188, v188, v182, v183
	v_max3_f32 v136, v188, v184, v135
	ds_bpermute_b32 v178, v142, v136
	s_waitcnt lgkmcnt(0)
	v_max_f32_e32 v178, v178, v178
	v_max_f32_e32 v136, v136, v178
	ds_bpermute_b32 v178, v143, v136
	s_waitcnt lgkmcnt(0)
	v_max3_f32 v185, v176, v136, v178
	v_sub_f32_e32 v136, v186, v185
	v_mul_f32_e32 v136, 0x3fb8aa3b, v136
	v_exp_f32_e32 v178, v136
	v_sub_f32_e32 v136, v187, v185
	v_mul_f32_e32 v136, 0x3fb8aa3b, v136
	v_sub_f32_e32 v180, v180, v185
	v_exp_f32_e32 v179, v136
	v_mul_f32_e32 v180, 0x3fb8aa3b, v180
	v_sub_f32_e32 v181, v181, v185
	v_exp_f32_e32 v180, v180
	v_mul_f32_e32 v181, 0x3fb8aa3b, v181
	v_sub_f32_e32 v182, v182, v185
	v_sub_f32_e32 v136, v176, v185
	v_exp_f32_e32 v181, v181
	v_mul_f32_e32 v182, 0x3fb8aa3b, v182
	v_sub_f32_e32 v183, v183, v185
	v_sub_f32_e32 v184, v184, v185
	v_sub_f32_e32 v135, v135, v185
	v_mul_f32_e32 v136, 0x3fb8aa3b, v136
	v_add_f32_e32 v176, 0, v178
	v_exp_f32_e32 v182, v182
	v_mul_f32_e32 v183, 0x3fb8aa3b, v183
	v_mul_f32_e32 v184, 0x3fb8aa3b, v184
	v_mul_f32_e32 v135, 0x3fb8aa3b, v135
	v_add_f32_e32 v176, v179, v176
	v_exp_f32_e32 v183, v183
	v_exp_f32_e32 v184, v184
	v_exp_f32_e32 v135, v135
	v_exp_f32_e32 v136, v136
	v_add_f32_e32 v176, v180, v176
	v_add_f32_e32 v176, v181, v176
	v_add_f32_e32 v176, v182, v176
	v_add_f32_e32 v176, v183, v176
	v_cvt_pk_bf16_f32 v178, v178, v179
	v_cvt_pk_bf16_f32 v179, v180, v181
	v_cvt_pk_bf16_f32 v180, v182, v183
	v_cvt_pk_bf16_f32 v181, v184, v135
	v_pk_mul_f32 v[48:49], v[48:49], v[136:137] op_sel_hi:[1,0]
	v_pk_mul_f32 v[46:47], v[46:47], v[136:137] op_sel_hi:[1,0]
	v_pk_mul_f32 v[44:45], v[44:45], v[136:137] op_sel_hi:[1,0]
	v_pk_mul_f32 v[42:43], v[42:43], v[136:137] op_sel_hi:[1,0]
	v_pk_mul_f32 v[40:41], v[40:41], v[136:137] op_sel_hi:[1,0]
	v_pk_mul_f32 v[38:39], v[38:39], v[136:137] op_sel_hi:[1,0]
	v_pk_mul_f32 v[36:37], v[36:37], v[136:137] op_sel_hi:[1,0]
	v_pk_mul_f32 v[34:35], v[34:35], v[136:137] op_sel_hi:[1,0]
	v_mfma_f32_16x16x32_bf16 v[46:49], v[110:113], v[178:181], v[46:49]
	v_add_f32_e32 v176, v184, v176
	v_add_f32_e32 v135, v135, v176
	v_fmac_f32_e32 v135, v161, v136
	v_mfma_f32_16x16x32_bf16 v[42:45], v[102:105], v[178:181], v[42:45]
	v_mov_b32_e32 v176, v185
	v_mov_b32_e32 v161, v135
	v_mfma_f32_16x16x32_bf16 v[38:41], v[106:109], v[178:181], v[38:41]
	v_mfma_f32_16x16x32_bf16 v[34:37], v[98:101], v[178:181], v[34:37]
.LBB0_1608:
	s_cmp_lt_i32 s48, s16
	s_cselect_b64 s[8:9], -1, 0
	s_cmp_gt_i32 s47, s17
	s_cselect_b64 s[52:53], -1, 0
	s_or_b64 s[8:9], s[8:9], s[52:53]
	s_and_b64 vcc, exec, s[8:9]
	s_cbranch_vccnz .LBB0_1610
	s_waitcnt vmcnt(3) lgkmcnt(11)
	v_mfma_f32_16x16x32_bf16 v[178:181], v[122:125], v[78:81], 0
	v_add_u32_e32 v209, 0xffffff60, v0
	v_cvt_f32_i32_e32 v208, v209
	s_waitcnt vmcnt(2) lgkmcnt(9)
	v_mfma_f32_16x16x32_bf16 v[178:181], v[126:129], v[82:85], v[178:181]
	s_cmpk_lt_u32 s47, 0x800
	s_cselect_b32 s52, 0x43010000, 0xbf800000
	v_add_f32_e32 v193, 1.0, v208
	v_add_f32_e32 v194, 2.0, v208
	v_add_f32_e32 v195, 0x40400000, v208
	v_add_f32_e32 v196, 4.0, v208
	v_add_f32_e32 v197, 0x40a00000, v208
	v_add_f32_e32 v198, 0x40c00000, v208
	v_add_f32_e32 v199, 0x40e00000, v208
	v_mul_f32_e64 v200, |v208|, v137
	v_mul_f32_e64 v201, |v193|, v137
	v_mul_f32_e64 v202, |v194|, v137
	v_mul_f32_e64 v203, |v195|, v137
	v_mul_f32_e64 v204, |v196|, v137
	v_mul_f32_e64 v205, |v197|, v137
	v_mul_f32_e64 v206, |v198|, v137
	v_mul_f32_e64 v207, |v199|, v137
	v_mfma_f32_16x16x32_bf16 v[182:185], v[118:121], v[78:81], 0
	s_waitcnt lgkmcnt(8)
	v_mfma_f32_16x16x32_bf16 v[182:185], v[114:117], v[82:85], v[182:185]
	v_mul_f32_e32 v210, v134, v178
	v_mul_f32_e32 v211, v134, v179
	v_mul_f32_e32 v212, v134, v180
	v_mul_f32_e32 v213, v134, v181
	v_sub_f32_e32 v210, v210, v200
	v_sub_f32_e32 v211, v211, v201
	v_sub_f32_e32 v212, v212, v202
	v_sub_f32_e32 v213, v213, v203
	v_cmp_gt_f32_e64 vcc, s52, |v208|
	v_cmp_gt_f32_e64 s[8:9], s52, |v193|
	s_nop 0
	v_cndmask_b32_e32 v186, v158, v210, vcc
	v_cndmask_b32_e64 v187, v158, v211, s[8:9]
	v_cmp_gt_f32_e64 vcc, s52, |v194|
	v_cmp_gt_f32_e64 s[8:9], s52, |v195|
	s_nop 0
	v_cndmask_b32_e32 v180, v158, v212, vcc
	v_cndmask_b32_e64 v181, v158, v213, s[8:9]
	v_mul_f32_e32 v214, v134, v182
	v_mul_f32_e32 v215, v134, v183
	v_mul_f32_e32 v216, v134, v184
	v_mul_f32_e32 v217, v134, v185
	v_sub_f32_e32 v214, v214, v204
	v_sub_f32_e32 v215, v215, v205
	v_sub_f32_e32 v216, v216, v206
	v_sub_f32_e32 v217, v217, v207
	v_cmp_gt_f32_e64 vcc, s52, |v196|
	v_cmp_gt_f32_e64 s[8:9], s52, |v197|
	s_nop 0
	v_cndmask_b32_e32 v182, v158, v214, vcc
	v_cndmask_b32_e64 v183, v158, v215, s[8:9]
	v_cmp_gt_f32_e64 vcc, s52, |v198|
	v_cmp_gt_f32_e64 s[8:9], s52, |v199|
	s_nop 0
	v_cndmask_b32_e32 v184, v158, v216, vcc
	v_cndmask_b32_e64 v135, v158, v217, s[8:9]
	v_max3_f32 v188, v186, s39, v187
	v_max3_f32 v188, v188, v180, v181
	v_max3_f32 v188, v188, v182, v183
	v_max3_f32 v136, v188, v184, v135
	ds_bpermute_b32 v178, v142, v136
	s_waitcnt lgkmcnt(0)
	v_max_f32_e32 v178, v178, v178
	v_max_f32_e32 v136, v136, v178
	ds_bpermute_b32 v178, v143, v136
	s_waitcnt lgkmcnt(0)
	v_max3_f32 v185, v175, v136, v178
	v_sub_f32_e32 v136, v186, v185
	v_mul_f32_e32 v136, 0x3fb8aa3b, v136
	v_exp_f32_e32 v178, v136
	v_sub_f32_e32 v136, v187, v185
	v_mul_f32_e32 v136, 0x3fb8aa3b, v136
	v_sub_f32_e32 v180, v180, v185
	v_exp_f32_e32 v179, v136
	v_mul_f32_e32 v180, 0x3fb8aa3b, v180
	v_sub_f32_e32 v181, v181, v185
	v_exp_f32_e32 v180, v180
	v_mul_f32_e32 v181, 0x3fb8aa3b, v181
	v_sub_f32_e32 v182, v182, v185
	v_sub_f32_e32 v136, v175, v185
	v_exp_f32_e32 v181, v181
	v_mul_f32_e32 v182, 0x3fb8aa3b, v182
	v_sub_f32_e32 v183, v183, v185
	v_sub_f32_e32 v184, v184, v185
	v_sub_f32_e32 v135, v135, v185
	v_mul_f32_e32 v136, 0x3fb8aa3b, v136
	v_add_f32_e32 v175, 0, v178
	v_exp_f32_e32 v182, v182
	v_mul_f32_e32 v183, 0x3fb8aa3b, v183
	v_mul_f32_e32 v184, 0x3fb8aa3b, v184
	v_mul_f32_e32 v135, 0x3fb8aa3b, v135
	v_add_f32_e32 v175, v179, v175
	v_exp_f32_e32 v183, v183
	v_exp_f32_e32 v184, v184
	v_exp_f32_e32 v135, v135
	v_exp_f32_e32 v136, v136
	v_add_f32_e32 v175, v180, v175
	v_add_f32_e32 v175, v181, v175
	v_add_f32_e32 v175, v182, v175
	v_add_f32_e32 v175, v183, v175
	v_cvt_pk_bf16_f32 v178, v178, v179
	v_cvt_pk_bf16_f32 v179, v180, v181
	v_cvt_pk_bf16_f32 v180, v182, v183
	v_cvt_pk_bf16_f32 v181, v184, v135
	v_pk_mul_f32 v[32:33], v[32:33], v[136:137] op_sel_hi:[1,0]
	v_pk_mul_f32 v[30:31], v[30:31], v[136:137] op_sel_hi:[1,0]
	v_pk_mul_f32 v[28:29], v[28:29], v[136:137] op_sel_hi:[1,0]
	v_pk_mul_f32 v[26:27], v[26:27], v[136:137] op_sel_hi:[1,0]
	v_pk_mul_f32 v[24:25], v[24:25], v[136:137] op_sel_hi:[1,0]
	v_pk_mul_f32 v[22:23], v[22:23], v[136:137] op_sel_hi:[1,0]
	v_pk_mul_f32 v[20:21], v[20:21], v[136:137] op_sel_hi:[1,0]
	v_pk_mul_f32 v[18:19], v[18:19], v[136:137] op_sel_hi:[1,0]
	v_mfma_f32_16x16x32_bf16 v[30:33], v[110:113], v[178:181], v[30:33]
	v_add_f32_e32 v175, v184, v175
	v_add_f32_e32 v135, v135, v175
	v_fmac_f32_e32 v135, v159, v136
	v_mfma_f32_16x16x32_bf16 v[26:29], v[102:105], v[178:181], v[26:29]
	v_mov_b32_e32 v175, v185
	v_mov_b32_e32 v159, v135
	v_mfma_f32_16x16x32_bf16 v[22:25], v[106:109], v[178:181], v[22:25]
	v_mfma_f32_16x16x32_bf16 v[18:21], v[98:101], v[178:181], v[18:21]
